# w_out epilogue layer 0: LDS-DMA touch of all 16 row steps' f32 residual lines at the first step
# speedup vs baseline: 1.0006x; 1.0006x over previous
; __device__ __forceinline__ void st16_wt(void* p, u32x4 v) { asm volatile("global_store_dwordx4 %0, %1, off sc1\n\ts_nop 1" :: "v"(p), "v"(v) : "memory"); }
; __device__ __forceinline__ void st16_wt(void* p, f32x4 v) { asm volatile("global_store_dwordx4 %0, %1, off sc1\n\ts_nop 1" :: "v"(p), "v"(v) : "memory"); }
; __device__ __forceinline__ void st4_wt(float* p, float v) { asm volatile("global_store_dword %0, %1, off sc1\n\ts_nop 1" :: "v"(p), "v"(v) : "memory"); }
; __device__ __forceinline__ u32x4 pack8(const f32x4& a, const f32x4& b) { u32x4 w; w.x = cvt_pk_bf16(a[0], a[1]); w.y = cvt_pk_bf16(a[2], a[3]); w.z = cvt_pk_bf16(b[0], b[1]); w.w = cvt_pk_bf16(b[2], b[3]); return w; }
; __device__ __forceinline__ float hsq4(const f32x4& v) { return (v[0] * v[0] + v[1] * v[1]) + (v[2] * v[2] + v[3] * v[3]); }
; __device__ __forceinline__ float red_fq(float s) { s += shfl_xor_(s, 16); s += shfl_xor_(s, 32); return s; }
; __device__ __forceinline__ f32x4 unpk_lo(unsigned a, unsigned b) { return (f32x4){__uint_as_float(a << 16), __uint_as_float(a & 0xffff0000u), __uint_as_float(b << 16), __uint_as_float(b & 0xffff0000u)}; }
;     __device__ __forceinline__ void operator()(const f32x4 (&acc)[2][2][4][2], const Unit& u, int wr, int wc, int fr, int fq) const {
;     ...
;             for (int m = 0; m < 4; ++m) { const int row = u.pm * BM + ai * HALF + wr * 64 + m * 16 + fr;
;                 float s = 0.f;
; #pragma unroll
;                 for (int bj = 0; bj < 2; ++bj) { const size_t o = (size_t)row * DM + u.pn * 256 + bj * HALF + cb;
;                     f32x4 a0, a1;
;                     if (xin_f32) { a0 = *(const f32x4*)(xin_f32 + o); a1 = *(const f32x4*)(xin_f32 + o + 4); }
;                     else { const u32x4 w = rw[m][bj]; a0 = unpk_lo(w.x, w.y); a1 = unpk_lo(w.z, w.w); }
;                     a0 = a0 + acc[ai][bj][m][0]; a1 = a1 + acc[ai][bj][m][1];
;                     if (WT) st16_wt(xb + o, pack8(a0, a1)); else *(u32x4*)(xb + o) = pack8(a0, a1); s += hsq4(a0) + hsq4(a1); }
;                 s = red_fq(s); if (fq == 0) { if (WT) st4_wt(rsx + (size_t)row * 16 + u.pn * 4 + wc, s); else rsx[(size_t)row * 16 + u.pn * 4 + wc] = s; }
.LBB0_1531:
	v_lshlrev_b64 v[162:163], 10, v[180:181]
	v_lshl_add_u64 v[162:163], v[162:163], 0, v[182:183]
	v_lshl_add_u64 v[188:189], v[162:163], 0, s[54:55]
	s_and_b64 vcc, exec, s[6:7]
	v_lshl_add_u64 v[184:185], v[188:189], 2, s[24:25]
	s_cbranch_vccnz .LBB0_1606
	s_mov_b32 s98, m0
	s_mov_b32 m0, 0x1000
	v_add_co_u32_e32 v216, vcc, 0x200, v184
	v_addc_co_u32_e32 v217, vcc, 0, v185, vcc
	global_load_lds_dword v[216:217], off
	v_add_co_u32_e32 v216, vcc, 0x10000, v184
	v_addc_co_u32_e32 v217, vcc, 0, v185, vcc
	global_load_lds_dword v[216:217], off
	v_add_co_u32_e32 v216, vcc, 0x10200, v184
	v_addc_co_u32_e32 v217, vcc, 0, v185, vcc
	global_load_lds_dword v[216:217], off
	v_add_co_u32_e32 v216, vcc, 0x20000, v184
	v_addc_co_u32_e32 v217, vcc, 0, v185, vcc
	global_load_lds_dword v[216:217], off
	v_add_co_u32_e32 v216, vcc, 0x20200, v184
	v_addc_co_u32_e32 v217, vcc, 0, v185, vcc
	global_load_lds_dword v[216:217], off
	v_add_co_u32_e32 v216, vcc, 0x30000, v184
	v_addc_co_u32_e32 v217, vcc, 0, v185, vcc
	global_load_lds_dword v[216:217], off
	v_add_co_u32_e32 v216, vcc, 0x30200, v184
	v_addc_co_u32_e32 v217, vcc, 0, v185, vcc
	global_load_lds_dword v[216:217], off
	v_add_co_u32_e32 v216, vcc, 0x80000, v184
	v_addc_co_u32_e32 v217, vcc, 0, v185, vcc
	global_load_lds_dword v[216:217], off
	v_add_co_u32_e32 v216, vcc, 0x80200, v184
	v_addc_co_u32_e32 v217, vcc, 0, v185, vcc
	global_load_lds_dword v[216:217], off
	v_add_co_u32_e32 v216, vcc, 0x90000, v184
	v_addc_co_u32_e32 v217, vcc, 0, v185, vcc
	global_load_lds_dword v[216:217], off
	v_add_co_u32_e32 v216, vcc, 0x90200, v184
	v_addc_co_u32_e32 v217, vcc, 0, v185, vcc
	global_load_lds_dword v[216:217], off
	v_add_co_u32_e32 v216, vcc, 0xa0000, v184
	v_addc_co_u32_e32 v217, vcc, 0, v185, vcc
	global_load_lds_dword v[216:217], off
	v_add_co_u32_e32 v216, vcc, 0xa0200, v184
	v_addc_co_u32_e32 v217, vcc, 0, v185, vcc
	global_load_lds_dword v[216:217], off
	v_add_co_u32_e32 v216, vcc, 0xb0000, v184
	v_addc_co_u32_e32 v217, vcc, 0, v185, vcc
	global_load_lds_dword v[216:217], off
	v_add_co_u32_e32 v216, vcc, 0xb0200, v184
	v_addc_co_u32_e32 v217, vcc, 0, v185, vcc
	global_load_lds_dword v[216:217], off
	s_mov_b32 m0, s98
	global_load_dwordx4 v[166:169], v[184:185], off offset:16
	global_load_dwordx4 v[162:165], v[184:185], off
	s_waitcnt vmcnt(0)
	s_cbranch_execnz .LBB0_1534
